# v55 plus M0 save and restore dropped around the ten LDS-DMA issues of the attention prologue and peeled tail steps
# baseline (speedup 1.0000x reference)
; __device__ __forceinline__ int otid() { int t = threadIdx.x; asm volatile("" : "+v"(t)); return t; }
; #define WAIT_BAR(N) asm volatile("s_waitcnt vmcnt(" #N ") lgkmcnt(0)\n\ts_barrier":::"memory")
;   #define DMA_K(t,slot) glds16(ksrc+(long)(t)*KVBLK*KVP,(unsigned)__builtin_amdgcn_readfirstlane(kdst+(slot)))
;   #define DMA_V(t,slot) glds16(vsrc+(long)(t)*KVBLK*KVP,(unsigned)__builtin_amdgcn_readfirstlane(vdst+(slot)))
;   #define CMASK(P0,P1,t) do{}while(0)
;   #define CMASK(P0,P1,t) do{}while(0)
;   #define CMASK(P0,P1,t) do{}while(0)
; template<int THRL> __device__ __forceinline__ void attn_unit(const bf16*Qu,const bf16*__restrict__ Kh,const bf16*__restrict__ Vh,bf16*Ou,const int NT,const float shift,char*shm){
;   const int tid=otid(),lane=tid&63,r32=lane&31,hi=lane>>5; const int wid=__builtin_amdgcn_readfirstlane(tid>>6);
;   const bf16*Qw=Qu+(long)wid*QBLK*QP;
;   const unsigned lds0=(unsigned)(uintptr_t)shm;
;   float*wsf=(float*)(shm+LDS_WS)+wid*64;
;   const bf16*ksrc=Kh+(long)lane*KVP+wid*8;
;   const bf16*vsrc=Vh+(long)(16*(wid&3)+(lane>>2))*KVP+(wid>>2)*32+(lane&3)*8;
;   const unsigned kdst=lds0+LDS_K+wid*1024, vdst=lds0+LDS_V+wid*1024;
;     ...
;   const int vb0=(int)(lds0+LDS_V)+((lane>>4)&1)*32+(lane&3)*8+(4*hi+((lane&15)>>2))*64;
;   const char*Kbase=shm+LDS_K; bf16x8 kf[8];
;   const lds_cptr shm3=(lds_cptr)shm; const lds_cptr kp0=shm3+LDS_K+hi*1024+r32*16; const lds_cptr vp0=shm3+LDS_V+((lane>>4)&1)*32+(lane&3)*8+(4*hi+((lane&15)>>2))*64;
;   DMA_K(0,0);DMA_V(0,0);DMA_K(1,SLOTB);
;   bf16x8 qr[4];
;   #pragma unroll
;   for(int d0=0;d0<4;++d0)qr[d0]=*reinterpret_cast<const bf16x8*>(&Qw[(long)r32*QP+d0*16+hi*8]);
;   float mhat=0.f,l_reg=0.f;f32x16 o[2];o[0]=f32x16{};o[1]=f32x16{};f32x16 negm=f32x16{};asm volatile("":"+v"(negm));
;     ...
;   bool resc=false;
;     ...
;   f32x16 pA0,pA1,pB0,pB1;
;   int sl_prev=0,sl_cur=0,sl_next=SLOTB;
;     ...
;   DMA_K(2,2*SLOTB);
;   WAIT_BAR(3);
;   qkt(pA0,pA1,Kbase,qr,negm,r32,hi);asm volatile("s_nop 15\n\ts_nop 7":"+v"(pA0),"+v"(pA1));CMASK(pA0,pA1,0);
;   START(pA0,pA1);
;   _Pragma("unroll") for(int r=0;r<16;++r)pA1[r]=__builtin_amdgcn_exp2f(pA1[r]);
;   WAIT_BAR(0);
.LBB0_616:
	s_lshl_b32 s4, s84, 1
	s_ashr_i32 s5, s82, 2
	s_add_i32 s6, s4, s5
	v_readlane_b32 s4, v246, 62
	v_readlane_b32 s5, v246, 63
	s_lshl_b64 s[4:5], s[4:5], 11
	s_add_u32 s7, s57, s4
	s_addc_u32 s24, s58, s5
	s_lshl_b32 s4, s82, 6
	s_ashr_i32 s5, s4, 31
	s_lshl_b64 s[48:49], s[4:5], 1
	s_add_u32 s26, s7, s48
	s_addc_u32 s27, s24, s49
	s_mul_hi_i32 s7, s6, 0x208000
	s_mul_i32 s6, s6, 0x208000
	s_add_u32 s4, s59, s6
	s_addc_u32 s5, s60, s7
	v_mov_b32_e32 v42, v216
	s_add_u32 s6, s61, s6
	s_addc_u32 s7, s62, s7
	v_readfirstlane_b32 s69, v42
	s_ashr_i32 s44, s69, 6
	s_ashr_i32 s45, s44, 31
	v_and_b32_e32 v238, 63, v42
	s_lshl_b64 s[24:25], s[44:45], 16
	s_add_u32 s24, s26, s24
	v_lshlrev_b32_e32 v0, 4, v42
	s_addc_u32 s25, s27, s25
	v_lshl_add_u64 v[2:3], s[4:5], 0, v[0:1]
	s_mov_b32 s4, 0
	s_ashr_i32 s5, s4, 31
	v_lshl_add_u64 v[212:213], s[4:5], 1, v[2:3]
	s_lshl_b32 s4, s44, 4
	v_bfe_u32 v0, v42, 2, 4
	v_and_or_b32 v0, s4, 48, v0
	s_ashr_i32 s4, s69, 3
	s_andn2_b32 s4, s4, 31
	v_lshlrev_b32_e32 v0, 7, v0
	s_ashr_i32 s5, s4, 31
	s_lshl_b32 s70, s44, 10
	v_lshl_add_u64 v[2:3], s[6:7], 0, v[0:1]
	v_lshlrev_b32_e32 v239, 3, v42
	s_cmp_lg_u32 0, -1
	v_lshl_add_u64 v[2:3], s[4:5], 1, v[2:3]
	v_and_b32_e32 v242, 24, v239
	s_cselect_b32 s4, 0, 0
	v_and_b32_e32 v240, 31, v42
	v_lshlrev_b32_e32 v0, 4, v42
	s_add_i32 s70, s70, s4
	s_mov_b32 m0, s70
	s_nop 0
	global_load_lds_dwordx4 v[212:213], off
	v_bfe_u32 v241, v42, 5, 1
	v_lshl_add_u64 v[214:215], s[6:7], 0, v[0:1]
	s_add_i32 s71, s70, 0x6000
	s_mov_b32 m0, s71
	s_nop 0
	global_load_lds_dwordx4 v[214:215], off
	s_mov_b64 s[26:27], 0x2000
	v_lshlrev_b32_e32 v0, 11, v240
	v_lshl_add_u64 v[2:3], v[212:213], 0, s[26:27]
	s_add_i32 s4, s70, 0x2000
	s_mov_b32 m0, s4
	s_nop 0
	global_load_lds_dwordx4 v[2:3], off
	v_lshl_or_b32 v0, v241, 4, v0
	global_load_dwordx4 v[150:153], v0, s[24:25]
	global_load_dwordx4 v[138:141], v0, s[24:25] offset:32
	global_load_dwordx4 v[134:137], v0, s[24:25] offset:64
	global_load_dwordx4 v[130:133], v0, s[24:25] offset:96
	v_mov_b32_e32 v2, v1
	v_mov_b32_e32 v3, v1
	v_mov_b32_e32 v4, v1
	v_mov_b32_e32 v5, v1
	v_mov_b32_e32 v6, v1
	v_mov_b32_e32 v7, v1
	v_mov_b32_e32 v8, v1
	v_mov_b32_e32 v9, v1
	v_mov_b32_e32 v10, v1
	v_mov_b32_e32 v11, v1
	v_mov_b32_e32 v12, v1
	v_mov_b32_e32 v13, v1
	v_mov_b32_e32 v14, v1
	v_mov_b32_e32 v15, v1
	v_lshlrev_b32_e32 v0, 10, v241
	v_lshlrev_b32_e32 v16, 4, v240
	v_add3_u32 v244, 0, v0, v16
	v_mov_b32_e32 v0, v1
	v_mov_b64_e32 v[16:17], v[14:15]
	v_mov_b64_e32 v[14:15], v[12:13]
	v_mov_b64_e32 v[12:13], v[10:11]
	v_mov_b64_e32 v[10:11], v[8:9]
	v_mov_b64_e32 v[8:9], v[6:7]
	v_mov_b64_e32 v[6:7], v[4:5]
	v_mov_b64_e32 v[4:5], v[2:3]
	v_mov_b64_e32 v[2:3], v[0:1]
	v_lshl_add_u64 v[18:19], v[212:213], 0, s[72:73]
	s_add_i32 s4, s70, 0x4000
	s_mov_b32 m0, s4
	s_nop 0
	global_load_lds_dwordx4 v[18:19], off
	s_waitcnt vmcnt(3) lgkmcnt(0)
	s_barrier
	ds_read_b128 v[34:37], v244
	ds_read_b128 v[38:41], v244 offset:512
	v_lshlrev_b32_e32 v0, 1, v42
	v_and_b32_e32 v243, 32, v0
	s_mov_b64 s[34:35], 0x6000
	v_add_u32_e32 v50, 0, v243
	s_mov_b32 s5, 1
	s_mov_b32 s4, 0
	s_movk_i32 s31, 0x2000
	s_mov_b32 s24, 0
	s_movk_i32 s76, 0x4000
	s_waitcnt vmcnt(3) lgkmcnt(1)
	v_mfma_f32_32x32x16_bf16 v[18:33], v[34:37], v[150:153], v[2:17]
	s_waitcnt lgkmcnt(0)
	v_mfma_f32_32x32x16_bf16 v[2:17], v[38:41], v[150:153], v[2:17]
	ds_read_b128 v[34:37], v244 offset:2048
	ds_read_b128 v[38:41], v244 offset:2560
	s_waitcnt vmcnt(2) lgkmcnt(1)
	v_mfma_f32_32x32x16_bf16 v[18:33], v[34:37], v[138:141], v[18:33]
	s_waitcnt lgkmcnt(0)
	v_mfma_f32_32x32x16_bf16 v[2:17], v[38:41], v[138:141], v[2:17]
	ds_read_b128 v[34:37], v244 offset:4096
	ds_read_b128 v[38:41], v244 offset:4608
	s_waitcnt vmcnt(1) lgkmcnt(1)
	v_mfma_f32_32x32x16_bf16 v[18:33], v[34:37], v[134:137], v[18:33]
	ds_read_b128 v[34:37], v244 offset:6144
	s_waitcnt lgkmcnt(1)
	v_mfma_f32_32x32x16_bf16 v[2:17], v[38:41], v[134:137], v[2:17]
	ds_read_b128 v[38:41], v244 offset:6656
	s_waitcnt vmcnt(0) lgkmcnt(1)
	v_mfma_f32_32x32x16_bf16 v[18:33], v[34:37], v[130:133], v[18:33]
	v_add_f32_e32 v34, v1, v237
	v_lshlrev_b32_e32 v35, 4, v42
	v_xor_b32_e32 v34, 0x80000000, v34
	v_and_b32_e32 v0, 0xc0, v35
	v_mov_b32_e32 v35, v34
	v_mov_b32_e32 v36, v34
	v_mov_b32_e32 v37, v34
	s_waitcnt lgkmcnt(0)
	v_mfma_f32_32x32x16_bf16 v[2:17], v[38:41], v[130:133], v[2:17]
	s_nop 15
	s_nop 7
	v_mov_b32_e32 v38, v34
	v_mov_b32_e32 v39, v34
	v_mov_b32_e32 v40, v34
	v_mov_b32_e32 v41, v34
	v_mov_b32_e32 v42, v34
	v_mov_b32_e32 v43, v34
	v_mov_b32_e32 v44, v34
	v_mov_b32_e32 v45, v34
	v_mov_b32_e32 v46, v34
	v_mov_b32_e32 v47, v34
	v_mov_b32_e32 v48, v34
	v_mov_b32_e32 v49, v34
	v_sub_f32_e32 v2, v2, v237
	v_sub_f32_e32 v3, v3, v237
	s_waitcnt vmcnt(0) lgkmcnt(0)
	s_barrier
; #define WAIT_BAR(N) asm volatile("s_waitcnt vmcnt(" #N ") lgkmcnt(0)\n\ts_barrier":::"memory")
;   #define DMA_K(t,slot) glds16(ksrc+(long)(t)*KVBLK*KVP,(unsigned)__builtin_amdgcn_readfirstlane(kdst+(slot)))
;   #define DMA_V(t,slot) glds16(vsrc+(long)(t)*KVBLK*KVP,(unsigned)__builtin_amdgcn_readfirstlane(vdst+(slot)))
;   #define CMASK(P0,P1,t) do{}while(0)
;   #define ROT() do{sl_prev=sl_cur;sl_cur=sl_next;sl_next=(sl_next==(NSLOT-1)*SLOTB)?0:sl_next+SLOTB;}while(0)
;   #define CMASK(P0,P1,t) do{}while(0)
;   #define CMASK(P0,P1,t) do{}while(0)
; template<int THRL> __device__ __forceinline__ void attn_unit(const bf16*Qu,const bf16*__restrict__ Kh,const bf16*__restrict__ Vh,bf16*Ou,const int NT,const float shift,char*shm){
;     ...
;   f32x16 pA0,pA1,pB0,pB1;
;   int sl_prev=0,sl_cur=0,sl_next=SLOTB;
;     ...
;   DMA_K(2,2*SLOTB);
;   WAIT_BAR(3);
;   qkt(pA0,pA1,Kbase,qr,negm,r32,hi);asm volatile("s_nop 15\n\ts_nop 7":"+v"(pA0),"+v"(pA1));CMASK(pA0,pA1,0);
;   START(pA0,pA1);
;   _Pragma("unroll") for(int r=0;r<16;++r)pA1[r]=__builtin_amdgcn_exp2f(pA1[r]);
;   WAIT_BAR(0);
;   DMA_K(3,0);DMA_V(1,SLOTB);
;   ROT();
;   kload8(kf,kp0+sl_cur);
;   WAIT_BAR(2);
;   s16x4 vlo[8],vhi[8]; u32x4 pw0,pw1,pw2,pw3;
;     ...
;   int t=1;
;     ...
;   for(;t+5<NT;t+=2){
	v_sub_f32_e32 v18, v18, v237
	v_sub_f32_e32 v19, v19, v237
	s_nop 0
	v_exp_f32_e32 v66, v2
	v_exp_f32_e32 v67, v3
	v_lshl_add_u64 v[2:3], v[212:213], 0, s[34:35]
	s_mov_b32 m0, s70
	s_nop 0
	global_load_lds_dwordx4 v[2:3], off
	v_lshl_add_u64 v[2:3], v[214:215], 0, s[26:27]
	s_add_i32 s6, s70, 0x8000
	s_mov_b32 m0, s6
	s_nop 0
	global_load_lds_dwordx4 v[2:3], off
	ds_read_b128 v[190:193], v244 offset:8192
	ds_read_b128 v[186:189], v244 offset:8704
	ds_read_b128 v[182:185], v244 offset:10240
	ds_read_b128 v[178:181], v244 offset:10752
	ds_read_b128 v[174:177], v244 offset:12288
	ds_read_b128 v[170:173], v244 offset:12800
	ds_read_b128 v[166:169], v244 offset:14336
	ds_read_b128 v[162:165], v244 offset:14848
	v_sub_f32_e32 v20, v20, v237
	v_sub_f32_e32 v4, v4, v237
	v_sub_f32_e32 v21, v21, v237
	v_sub_f32_e32 v5, v5, v237
	v_sub_f32_e32 v22, v22, v237
	v_sub_f32_e32 v6, v6, v237
	v_sub_f32_e32 v23, v23, v237
	v_sub_f32_e32 v7, v7, v237
	v_sub_f32_e32 v24, v24, v237
	v_sub_f32_e32 v8, v8, v237
	v_sub_f32_e32 v25, v25, v237
	v_sub_f32_e32 v9, v9, v237
	v_sub_f32_e32 v26, v26, v237
	v_sub_f32_e32 v10, v10, v237
	v_sub_f32_e32 v27, v27, v237
	v_sub_f32_e32 v11, v11, v237
	v_sub_f32_e32 v28, v28, v237
	v_sub_f32_e32 v12, v12, v237
	v_sub_f32_e32 v29, v29, v237
	v_sub_f32_e32 v13, v13, v237
	v_sub_f32_e32 v30, v30, v237
	v_sub_f32_e32 v14, v14, v237
	v_sub_f32_e32 v31, v31, v237
	v_sub_f32_e32 v15, v15, v237
	v_sub_f32_e32 v32, v32, v237
	v_sub_f32_e32 v16, v16, v237
	v_sub_f32_e32 v33, v33, v237
	v_sub_f32_e32 v17, v17, v237
	v_exp_f32_e32 v82, v18
	v_exp_f32_e32 v83, v19
	v_exp_f32_e32 v84, v20
	v_exp_f32_e32 v85, v21
	v_exp_f32_e32 v86, v22
	v_exp_f32_e32 v87, v23
	v_exp_f32_e32 v88, v24
	v_exp_f32_e32 v89, v25
	v_exp_f32_e32 v90, v26
	v_exp_f32_e32 v91, v27
	v_exp_f32_e32 v92, v28
	v_exp_f32_e32 v93, v29
	v_exp_f32_e32 v94, v30
	v_exp_f32_e32 v95, v31
	v_exp_f32_e32 v96, v32
	v_exp_f32_e32 v97, v33
	v_exp_f32_e32 v68, v4
	v_exp_f32_e32 v69, v5
	v_exp_f32_e32 v70, v6
	v_exp_f32_e32 v71, v7
	v_exp_f32_e32 v72, v8
	v_exp_f32_e32 v73, v9
	v_exp_f32_e32 v74, v10
	v_exp_f32_e32 v75, v11
	v_exp_f32_e32 v76, v12
	v_exp_f32_e32 v77, v13
	v_exp_f32_e32 v78, v14
	v_exp_f32_e32 v79, v15
	v_exp_f32_e32 v80, v16
	v_exp_f32_e32 v81, v17
	s_waitcnt vmcnt(2) lgkmcnt(0)
	s_barrier
	v_lshl_or_b32 v0, v241, 8, v0
	v_add3_u32 v245, v50, v242, v0
	s_cmp_lt_i32 s91, 6
	s_cbranch_scc1 .LBB0_620
	s_mov_b64 s[4:5], 0xa000
	v_mov_b32_e32 v199, v245
	v_add_u32_e32 v200, 0x2000, v245
	v_add_u32_e32 v201, 0x4000, v245
	v_mov_b32_e32 v202, v244
	v_add_u32_e32 v203, 0x2000, v244
	v_add_u32_e32 v204, 0x4000, v244
	v_mov_b32_e32 v50, 0
	v_mov_b32_e32 v194, 0
	v_mov_b32_e32 v195, 0
	v_mov_b32_e32 v196, 0
	v_lshlrev_b32_e32 v197, 4, v238
	v_readfirstlane_b32 s98, v212
	v_readfirstlane_b32 s99, v213
	v_readfirstlane_b32 s100, v214
	v_readfirstlane_b32 s101, v215
	s_add_u32 s98, s98, 0x8000
	s_addc_u32 s99, s99, 0
	s_add_u32 s100, s100, 0x4000
	s_addc_u32 s101, s101, 0
	s_sub_u32 s6, s100, s98
	v_add_u32_e32 v205, s6, v197
	s_mov_b32 s26, 6
	v_mov_b32_e32 v2, 0
	v_mov_b32_e32 v3, v50
	v_mov_b32_e32 v4, v50
	v_mov_b32_e32 v5, v50
	v_mov_b32_e32 v6, v50
	v_mov_b32_e32 v7, v50
	v_mov_b32_e32 v8, v50
	v_mov_b32_e32 v9, v50
	v_mov_b32_e32 v10, v50
	v_mov_b32_e32 v11, v50
	v_mov_b32_e32 v12, v50
	v_mov_b32_e32 v13, v50
	v_mov_b32_e32 v14, v50
	v_mov_b32_e32 v15, v50
	v_mov_b32_e32 v16, v50
	v_mov_b32_e32 v17, v50
	v_mov_b32_e32 v18, 0
	v_mov_b32_e32 v19, v50
	v_mov_b32_e32 v20, v50
	v_mov_b32_e32 v21, v50
	v_mov_b32_e32 v22, v50
	v_mov_b32_e32 v23, v50
	v_mov_b32_e32 v24, v50
	v_mov_b32_e32 v25, v50
	v_mov_b32_e32 v26, v50
	v_mov_b32_e32 v27, v50
	v_mov_b32_e32 v28, v50
	v_mov_b32_e32 v29, v50
	v_mov_b32_e32 v30, v50
	v_mov_b32_e32 v31, v50
	v_mov_b32_e32 v32, v50
	v_mov_b32_e32 v33, v50
	s_branch .LBB0_618

;   #define RESC() do{ if(resc){ asm volatile("s_waitcnt lgkmcnt(0)":::"memory"); \
;       _Pragma("unroll") for(int d_=0;d_<2;++d_) _Pragma("unroll") for(int r=0;r<16;++r)o[d_][r]*=wsf[crow(r,hi)]; } }while(0)
;   #define ROT() do{sl_prev=sl_cur;sl_cur=sl_next;sl_next=(sl_next==(NSLOT-1)*SLOTB)?0:sl_next+SLOTB;}while(0)
;   #define ENDW(tt) do{ if((tt)+3<NT){WAIT_BAR(2);} else if((tt)+2<NT){WAIT_BAR(1);} else {WAIT_BAR(0);} }while(0)
; template<int THRL> __device__ __forceinline__ void attn_unit(const bf16*Qu,const bf16*__restrict__ Kh,const bf16*__restrict__ Vh,bf16*Ou,const int NT,const float shift,char*shm){
;     ...
;   for(;t+1<NT;t+=2){
;     STEP(pB0,pB1,pA0,pA1,t,(t+3<NT),(t+1<NT),(t+1<NT));       ENDW(t);   RESC(); ROT();
;     STEP(pA0,pA1,pB0,pB1,t+1,(t+4<NT),(t+2<NT),(t+2<NT));     ENDW(t+1); RESC(); ROT();
.LBB0_623:
	v_add_u32_e32 v51, s4, v245
	ds_read_b64_tr_b16 v[194:195], v51 offset:24576
	ds_read_b64_tr_b16 v[196:197], v51 offset:25088
	s_waitcnt lgkmcnt(9)
	v_mfma_f32_32x32x16_bf16 v[114:129], v[190:193], v[150:153], v[34:49]
	v_add_f32_e32 v52, v82, v83
	v_add_f32_e32 v52, v84, v52
	v_add_f32_e32 v52, v85, v52
	v_add_f32_e32 v52, v86, v52
	v_add_f32_e32 v52, v87, v52
	v_cvt_pk_bf16_f32 v158, v82, v83
	v_cvt_pk_bf16_f32 v159, v84, v85
	ds_read_b64_tr_b16 v[82:83], v51 offset:28672
	ds_read_b64_tr_b16 v[84:85], v51 offset:29184
	s_waitcnt lgkmcnt(10)
	v_mfma_f32_32x32x16_bf16 v[98:113], v[186:189], v[150:153], v[34:49]
	v_add_f32_e32 v52, v88, v52
	v_add_f32_e32 v52, v89, v52
	v_add_f32_e32 v52, v90, v52
	v_add_f32_e32 v56, v91, v52
	v_cvt_pk_bf16_f32 v160, v86, v87
	v_cvt_pk_bf16_f32 v161, v88, v89
	ds_read_b64_tr_b16 v[52:53], v51 offset:25600
	ds_read_b64_tr_b16 v[54:55], v51 offset:26112
	s_waitcnt lgkmcnt(11)
	v_mfma_f32_32x32x16_bf16 v[114:129], v[182:185], v[138:141], v[114:129]
	v_add_f32_e32 v56, v92, v56
	v_add_f32_e32 v56, v93, v56
	v_add_f32_e32 v56, v94, v56
	v_add_f32_e32 v60, v95, v56
	v_cvt_pk_bf16_f32 v154, v90, v91
	v_cvt_pk_bf16_f32 v155, v92, v93
	ds_read_b64_tr_b16 v[56:57], v51 offset:29696
	ds_read_b64_tr_b16 v[58:59], v51 offset:30208
	s_waitcnt lgkmcnt(12)
	v_mfma_f32_32x32x16_bf16 v[98:113], v[178:181], v[138:141], v[98:113]
	v_add_f32_e32 v60, v96, v60
	v_add_f32_e32 v60, v97, v60
	v_add_f32_e32 v60, v66, v60
	v_add_f32_e32 v64, v67, v60
	v_cvt_pk_bf16_f32 v156, v94, v95
	v_cvt_pk_bf16_f32 v157, v96, v97
	ds_read_b64_tr_b16 v[60:61], v51 offset:26624
	ds_read_b64_tr_b16 v[62:63], v51 offset:27136
	s_waitcnt lgkmcnt(13)
	v_mfma_f32_32x32x16_bf16 v[114:129], v[174:177], v[134:137], v[114:129]
	v_add_f32_e32 v64, v68, v64
	v_add_f32_e32 v64, v69, v64
	v_add_f32_e32 v64, v70, v64
	v_add_f32_e32 v86, v71, v64
	v_cvt_pk_bf16_f32 v146, v66, v67
	v_cvt_pk_bf16_f32 v147, v68, v69
	ds_read_b64_tr_b16 v[64:65], v51 offset:30720
	ds_read_b64_tr_b16 v[66:67], v51 offset:31232
	s_waitcnt lgkmcnt(14)
	v_mfma_f32_32x32x16_bf16 v[98:113], v[170:173], v[134:137], v[98:113]
	v_add_f32_e32 v68, v72, v86
	v_add_f32_e32 v68, v73, v68
	v_add_f32_e32 v68, v74, v68
	v_add_f32_e32 v86, v75, v68
	v_cvt_pk_bf16_f32 v148, v70, v71
	v_cvt_pk_bf16_f32 v149, v72, v73
	ds_read_b64_tr_b16 v[68:69], v51 offset:27648
	ds_read_b64_tr_b16 v[70:71], v51 offset:28160
	s_waitcnt lgkmcnt(14)
	v_mfma_f32_32x32x16_bf16 v[114:129], v[166:169], v[130:133], v[114:129]
	v_add_f32_e32 v72, v76, v86
	v_add_f32_e32 v72, v77, v72
	v_add_f32_e32 v72, v78, v72
	v_add_f32_e32 v86, v79, v72
	v_cvt_pk_bf16_f32 v142, v74, v75
	v_cvt_pk_bf16_f32 v143, v76, v77
	ds_read_b64_tr_b16 v[72:73], v51 offset:31744
	ds_read_b64_tr_b16 v[74:75], v51 offset:32256
	v_mfma_f32_32x32x16_bf16 v[98:113], v[162:165], v[130:133], v[98:113]
	v_add_f32_e32 v51, v80, v86
	v_add_f32_e32 v51, v81, v51
	v_add_f32_e32 v51, 0, v51
	v_cvt_pk_bf16_f32 v144, v78, v79
	v_cvt_pk_bf16_f32 v145, v80, v81
	s_add_i32 s34, s30, -1
	s_cmp_ge_i32 s34, s91
	s_cselect_b64 s[50:51], -1, 0
	s_and_b64 vcc, exec, s[50:51]
	s_cbranch_vccnz .LBB0_625
	s_mov_b32 s35, s81
	s_lshl_b64 s[4:5], s[34:35], 13
	v_lshl_add_u64 v[76:77], v[212:213], 0, s[4:5]
	s_add_i32 s4, s31, s70
	s_mov_b32 m0, s4
	s_nop 0
	global_load_lds_dwordx4 v[76:77], off
.LBB0_625:
	s_add_i32 s80, s30, -3
	s_lshl_b64 s[4:5], s[80:81], 13
	v_lshl_add_u64 v[76:77], v[214:215], 0, s[4:5]
	s_add_i32 s4, s76, s71
	s_mov_b32 m0, s4
	s_nop 0
	global_load_lds_dwordx4 v[76:77], off
	s_waitcnt lgkmcnt(14)
	v_mfma_f32_32x32x16_bf16 v[2:17], v[158:161], v[194:197], v[2:17]
	v_exp_f32_e32 v114, v114
	v_exp_f32_e32 v115, v115
	v_exp_f32_e32 v116, v116
	v_exp_f32_e32 v117, v117
	s_waitcnt lgkmcnt(12)
	v_mfma_f32_32x32x16_bf16 v[18:33], v[158:161], v[82:85], v[18:33]
	v_exp_f32_e32 v118, v118
	v_exp_f32_e32 v119, v119
	v_exp_f32_e32 v120, v120
	v_exp_f32_e32 v121, v121
	v_add_u32_e32 v76, s76, v244
	ds_read_b128 v[190:193], v76
	ds_read_b128 v[186:189], v76 offset:512
	s_waitcnt lgkmcnt(12)
	v_mfma_f32_32x32x16_bf16 v[2:17], v[154:157], v[52:55], v[2:17]
	v_exp_f32_e32 v122, v122
	v_exp_f32_e32 v123, v123
	v_exp_f32_e32 v124, v124
	v_exp_f32_e32 v125, v125
	ds_read_b128 v[182:185], v76 offset:2048
	ds_read_b128 v[178:181], v76 offset:2560
	s_waitcnt lgkmcnt(12)
	v_mfma_f32_32x32x16_bf16 v[18:33], v[154:157], v[56:59], v[18:33]
	v_exp_f32_e32 v126, v126
	v_exp_f32_e32 v127, v127
	v_exp_f32_e32 v128, v128
	v_exp_f32_e32 v129, v129
	ds_read_b128 v[174:177], v76 offset:4096
	ds_read_b128 v[170:173], v76 offset:4608
	s_waitcnt lgkmcnt(12)
	v_mfma_f32_32x32x16_bf16 v[2:17], v[146:149], v[60:63], v[2:17]
	v_exp_f32_e32 v98, v98
	v_exp_f32_e32 v99, v99
	v_exp_f32_e32 v100, v100
	v_exp_f32_e32 v101, v101
	ds_read_b128 v[166:169], v76 offset:6144
	ds_read_b128 v[162:165], v76 offset:6656
	s_waitcnt lgkmcnt(12)
	v_mfma_f32_32x32x16_bf16 v[18:33], v[146:149], v[64:67], v[18:33]
	v_exp_f32_e32 v102, v102
	v_exp_f32_e32 v103, v103
	v_exp_f32_e32 v104, v104
	v_exp_f32_e32 v105, v105
	s_waitcnt lgkmcnt(10)
	v_mfma_f32_32x32x16_bf16 v[2:17], v[142:145], v[68:71], v[2:17]
	v_exp_f32_e32 v106, v106
	v_exp_f32_e32 v107, v107
	v_exp_f32_e32 v108, v108
	v_exp_f32_e32 v109, v109
	s_waitcnt lgkmcnt(8)
	v_mfma_f32_32x32x16_bf16 v[18:33], v[142:145], v[72:75], v[18:33]
	v_exp_f32_e32 v110, v110
	v_exp_f32_e32 v111, v111
	v_exp_f32_e32 v112, v112
	v_exp_f32_e32 v113, v113
	s_mov_b64 s[38:39], -1
	s_and_b64 vcc, exec, s[50:51]
	s_cbranch_vccz .LBB0_631
	s_add_i32 s4, s30, -2
	s_cmp_ge_i32 s4, s91
	s_cbranch_scc0 .LBB0_628
	s_waitcnt vmcnt(0) lgkmcnt(0)
	s_barrier
	s_mov_b64 s[38:39], 0

;   #define RESC() do{ if(resc){ asm volatile("s_waitcnt lgkmcnt(0)":::"memory"); \
;       _Pragma("unroll") for(int d_=0;d_<2;++d_) _Pragma("unroll") for(int r=0;r<16;++r)o[d_][r]*=wsf[crow(r,hi)]; } }while(0)
;   #define ROT() do{sl_prev=sl_cur;sl_cur=sl_next;sl_next=(sl_next==(NSLOT-1)*SLOTB)?0:sl_next+SLOTB;}while(0)
;   #define ENDW(tt) do{ if((tt)+3<NT){WAIT_BAR(2);} else if((tt)+2<NT){WAIT_BAR(1);} else {WAIT_BAR(0);} }while(0)
; template<int THRL> __device__ __forceinline__ void attn_unit(const bf16*Qu,const bf16*__restrict__ Kh,const bf16*__restrict__ Vh,bf16*Ou,const int NT,const float shift,char*shm){
;     ...
;     STEP(pA0,pA1,pB0,pB1,t+1,(t+4<NT),(t+2<NT),(t+2<NT));     ENDW(t+1); RESC(); ROT();
.LBB0_633:
	v_add_u32_e32 v54, s31, v245
	ds_read_b64_tr_b16 v[202:203], v54 offset:24576
	ds_read_b64_tr_b16 v[204:205], v54 offset:25088
	s_waitcnt lgkmcnt(9)
	v_mfma_f32_32x32x16_bf16 v[82:97], v[190:193], v[150:153], v[34:49]
	v_add_f32_e32 v52, v114, v115
	v_add_f32_e32 v52, v116, v52
	v_add_f32_e32 v52, v117, v52
	v_add_f32_e32 v52, v118, v52
	v_add_f32_e32 v52, v119, v52
	v_cvt_pk_bf16_f32 v158, v114, v115
	v_cvt_pk_bf16_f32 v159, v116, v117
	ds_read_b64_tr_b16 v[198:199], v54 offset:28672
	ds_read_b64_tr_b16 v[200:201], v54 offset:29184
	s_waitcnt lgkmcnt(10)
	v_mfma_f32_32x32x16_bf16 v[66:81], v[186:189], v[150:153], v[34:49]
	v_add_f32_e32 v52, v120, v52
	v_add_f32_e32 v52, v121, v52
	v_add_f32_e32 v52, v122, v52
	v_add_f32_e32 v52, v123, v52
	v_cvt_pk_bf16_f32 v160, v118, v119
	v_cvt_pk_bf16_f32 v161, v120, v121
	ds_read_b64_tr_b16 v[194:195], v54 offset:25600
	ds_read_b64_tr_b16 v[196:197], v54 offset:26112
	s_waitcnt lgkmcnt(11)
	v_mfma_f32_32x32x16_bf16 v[82:97], v[182:185], v[138:141], v[82:97]
	v_add_f32_e32 v52, v124, v52
	v_add_f32_e32 v52, v125, v52
	v_add_f32_e32 v52, v126, v52
	v_add_f32_e32 v52, v127, v52
	v_cvt_pk_bf16_f32 v154, v122, v123
	v_cvt_pk_bf16_f32 v155, v124, v125
	ds_read_b64_tr_b16 v[118:119], v54 offset:29696
	ds_read_b64_tr_b16 v[120:121], v54 offset:30208
	s_waitcnt lgkmcnt(12)
	v_mfma_f32_32x32x16_bf16 v[66:81], v[178:181], v[138:141], v[66:81]
	v_add_f32_e32 v52, v128, v52
	v_add_f32_e32 v52, v129, v52
	v_add_f32_e32 v52, v98, v52
	v_add_f32_e32 v52, v99, v52
	v_cvt_pk_bf16_f32 v156, v126, v127
	v_cvt_pk_bf16_f32 v157, v128, v129
	ds_read_b64_tr_b16 v[114:115], v54 offset:26624
	ds_read_b64_tr_b16 v[116:117], v54 offset:27136
	s_waitcnt lgkmcnt(13)
	v_mfma_f32_32x32x16_bf16 v[82:97], v[174:177], v[134:137], v[82:97]
	v_add_f32_e32 v52, v100, v52
	v_add_f32_e32 v52, v101, v52
	v_add_f32_e32 v52, v102, v52
	v_add_f32_e32 v52, v103, v52
	v_cvt_pk_bf16_f32 v146, v98, v99
	v_cvt_pk_bf16_f32 v147, v100, v101
	ds_read_b64_tr_b16 v[60:61], v54 offset:30720
	ds_read_b64_tr_b16 v[62:63], v54 offset:31232
	s_waitcnt lgkmcnt(14)
	v_mfma_f32_32x32x16_bf16 v[66:81], v[170:173], v[134:137], v[66:81]
	v_add_f32_e32 v52, v104, v52
	v_add_f32_e32 v52, v105, v52
	v_add_f32_e32 v52, v106, v52
	v_add_f32_e32 v52, v107, v52
	v_cvt_pk_bf16_f32 v148, v102, v103
	v_cvt_pk_bf16_f32 v149, v104, v105
	ds_read_b64_tr_b16 v[56:57], v54 offset:27648
	ds_read_b64_tr_b16 v[58:59], v54 offset:28160
	s_waitcnt lgkmcnt(14)
	v_mfma_f32_32x32x16_bf16 v[82:97], v[166:169], v[130:133], v[82:97]
	v_add_f32_e32 v52, v108, v52
	v_add_f32_e32 v52, v109, v52
	v_add_f32_e32 v52, v110, v52
	v_add_f32_e32 v64, v111, v52
	v_cvt_pk_bf16_f32 v142, v106, v107
	v_cvt_pk_bf16_f32 v143, v108, v109
	ds_read_b64_tr_b16 v[52:53], v54 offset:31744
	ds_read_b64_tr_b16 v[54:55], v54 offset:32256
	v_mfma_f32_32x32x16_bf16 v[66:81], v[162:165], v[130:133], v[66:81]
	v_add_f32_e32 v64, v112, v64
	v_add_f32_e32 v64, v113, v64
	v_add_f32_e32 v64, 0, v64
	v_cvt_pk_bf16_f32 v144, v110, v111
	v_cvt_pk_bf16_f32 v145, v112, v113
	s_cmp_ge_i32 s30, s91
	s_cselect_b64 s[52:53], -1, 0
	s_and_b64 vcc, exec, s[52:53]
	s_cbranch_vccnz .LBB0_635
	s_mov_b32 s31, s81
	s_lshl_b64 s[4:5], s[30:31], 13
	v_lshl_add_u64 v[98:99], v[212:213], 0, s[4:5]
	s_add_i32 s4, s76, s70
	s_mov_b32 m0, s4
	s_nop 0
	global_load_lds_dwordx4 v[98:99], off
.LBB0_635:
	s_add_i32 s4, s76, 0x2000
	s_cmpk_lg_i32 s76, 0x4000
	s_cselect_b32 s31, s4, 0
	s_add_i32 s80, s30, -2
	s_cmp_lt_i32 s80, s91
	s_cselect_b64 s[54:55], -1, 0
	s_cmp_ge_i32 s80, s91
	s_cbranch_scc1 .LBB0_637
	s_lshl_b64 s[4:5], s[80:81], 13
	v_lshl_add_u64 v[98:99], v[214:215], 0, s[4:5]
	s_add_i32 s4, s31, s71
	s_mov_b32 m0, s4
	s_nop 0
	global_load_lds_dwordx4 v[98:99], off
